# v_pk_mov_b32 accumulator zeroing extended to the remaining 6 GEMM loops (runs split at the in-block vmcnt wait)
# baseline (speedup 1.0000x reference)
; template <class Epi>
; __device__ __forceinline__ void gemm_phase(LAS unsigned char* lds, const Gemm g, const StaticOrder& S, const Epi& E) {
;     ...
;         const char* nA = has_next ? (const char*)g.A + (size_t)nxt.pm * tstepA : cA; const char* nB = has_next ? (const char*)g.Bt + (size_t)nxt.pn * tstepB : cB;
;         for (int t = 0; t < nt; t += 2) {
;             const bool last = (t == nt - 2);
;             const char* a1 = cA + (size_t)(t + 1) * kstep;
;             const char* a2 = last ? nA : cA + (size_t)(t + 2) * kstep; const char* b2 = last ? nB : cB + (size_t)(t + 2) * kstep;
;             const char* a3 = a2 + kstep; const char* b3 = b2 + kstep;
;     ...
; #pragma unroll
;         for (int a = 0; a < 2; ++a)
; #pragma unroll
;             for (int b = 0; b < 2; ++b)
; #pragma unroll
;                 for (int m = 0; m < 4; ++m)
; #pragma unroll
;                     for (int n = 0; n < 2; ++n) acc[a][b][m][n] = (f32x4){0.f, 0.f, 0.f, 0.f};
.LBB0_904:
	s_ashr_i32 s41, s40, 31
	s_lshl_b64 s[46:47], s[40:41], 19
	v_readlane_b32 s39, v254, 32
	s_add_u32 s52, s39, s46
	s_addc_u32 s53, s50, s47
	s_and_b64 s[46:47], s[16:17], exec
	s_cselect_b32 s41, s53, s63
	s_cselect_b32 s46, s52, s62
	s_ashr_i32 s39, s38, 31
	s_lshl_b64 s[56:57], s[38:39], 19
	s_add_u32 s56, s86, s56
	s_addc_u32 s57, s87, s57
	s_and_b64 s[68:69], s[16:17], exec
	s_cselect_b32 s39, s57, s65
	s_cselect_b32 s47, s56, s64
	s_add_u32 s62, s62, 0x40080
	s_addc_u32 s63, s63, 0
	s_add_u32 s59, s64, 0x100
	v_mov_b32_e32 v0, 0
	s_addc_u32 s80, s65, 0
	s_mov_b32 s81, -2
	v_mov_b32_e32 v1, v0
	v_pk_mov_b32 v[2:3], v[0:1], v[0:1]
	v_pk_mov_b32 v[4:5], v[0:1], v[0:1]
	v_pk_mov_b32 v[6:7], v[0:1], v[0:1]
	v_pk_mov_b32 v[8:9], v[0:1], v[0:1]
	v_pk_mov_b32 v[10:11], v[0:1], v[0:1]
	v_pk_mov_b32 v[12:13], v[0:1], v[0:1]
	v_pk_mov_b32 v[14:15], v[0:1], v[0:1]
	v_pk_mov_b32 v[16:17], v[0:1], v[0:1]
	v_pk_mov_b32 v[18:19], v[0:1], v[0:1]
	v_pk_mov_b32 v[20:21], v[0:1], v[0:1]
	v_pk_mov_b32 v[22:23], v[0:1], v[0:1]
	v_pk_mov_b32 v[24:25], v[0:1], v[0:1]
	v_pk_mov_b32 v[26:27], v[0:1], v[0:1]
	v_pk_mov_b32 v[28:29], v[0:1], v[0:1]
	v_pk_mov_b32 v[30:31], v[0:1], v[0:1]
	v_pk_mov_b32 v[32:33], v[0:1], v[0:1]
	v_pk_mov_b32 v[34:35], v[0:1], v[0:1]
	v_pk_mov_b32 v[36:37], v[0:1], v[0:1]
	v_pk_mov_b32 v[38:39], v[0:1], v[0:1]
	v_pk_mov_b32 v[40:41], v[0:1], v[0:1]
	v_pk_mov_b32 v[42:43], v[0:1], v[0:1]
	v_pk_mov_b32 v[44:45], v[0:1], v[0:1]
	v_pk_mov_b32 v[46:47], v[0:1], v[0:1]
	v_pk_mov_b32 v[48:49], v[0:1], v[0:1]
	v_pk_mov_b32 v[50:51], v[0:1], v[0:1]
	v_pk_mov_b32 v[52:53], v[0:1], v[0:1]
	v_pk_mov_b32 v[54:55], v[0:1], v[0:1]
	v_pk_mov_b32 v[56:57], v[0:1], v[0:1]
	v_pk_mov_b32 v[58:59], v[0:1], v[0:1]
	v_pk_mov_b32 v[104:105], v[0:1], v[0:1]
	v_pk_mov_b32 v[106:107], v[0:1], v[0:1]
	v_pk_mov_b32 v[112:113], v[0:1], v[0:1]
	v_pk_mov_b32 v[114:115], v[0:1], v[0:1]
	s_waitcnt vmcnt(0)
	v_pk_mov_b32 v[116:117], v[0:1], v[0:1]
	v_pk_mov_b32 v[118:119], v[0:1], v[0:1]
	v_pk_mov_b32 v[120:121], v[0:1], v[0:1]
	v_pk_mov_b32 v[122:123], v[0:1], v[0:1]
	v_pk_mov_b32 v[124:125], v[0:1], v[0:1]
	v_pk_mov_b32 v[126:127], v[0:1], v[0:1]
	v_pk_mov_b32 v[128:129], v[0:1], v[0:1]
	v_pk_mov_b32 v[130:131], v[0:1], v[0:1]
	v_pk_mov_b32 v[132:133], v[0:1], v[0:1]
	v_pk_mov_b32 v[134:135], v[0:1], v[0:1]
	v_pk_mov_b32 v[136:137], v[0:1], v[0:1]
	v_pk_mov_b32 v[138:139], v[0:1], v[0:1]
	v_pk_mov_b32 v[140:141], v[0:1], v[0:1]
	v_pk_mov_b32 v[142:143], v[0:1], v[0:1]
	v_pk_mov_b32 v[144:145], v[0:1], v[0:1]
	v_pk_mov_b32 v[146:147], v[0:1], v[0:1]
	v_pk_mov_b32 v[148:149], v[0:1], v[0:1]
	v_pk_mov_b32 v[150:151], v[0:1], v[0:1]
	v_pk_mov_b32 v[152:153], v[0:1], v[0:1]
	v_pk_mov_b32 v[154:155], v[0:1], v[0:1]
	v_pk_mov_b32 v[156:157], v[0:1], v[0:1]
	v_pk_mov_b32 v[158:159], v[0:1], v[0:1]
	v_pk_mov_b32 v[160:161], v[0:1], v[0:1]
	v_pk_mov_b32 v[162:163], v[0:1], v[0:1]
	v_pk_mov_b32 v[164:165], v[0:1], v[0:1]
	v_pk_mov_b32 v[166:167], v[0:1], v[0:1]
	v_pk_mov_b32 v[168:169], v[0:1], v[0:1]
	v_pk_mov_b32 v[170:171], v[0:1], v[0:1]
	v_pk_mov_b32 v[172:173], v[0:1], v[0:1]
	v_pk_mov_b32 v[174:175], v[0:1], v[0:1]

; template <class Epi>
; __device__ __forceinline__ void gemm_phase(LAS unsigned char* lds, const Gemm g, const StaticOrder& S, const Epi& E) {
;     ...
;         const char* nA = has_next ? (const char*)g.A + (size_t)nxt.pm * tstepA : cA; const char* nB = has_next ? (const char*)g.Bt + (size_t)nxt.pn * tstepB : cB;
;         for (int t = 0; t < nt; t += 2) {
;             const bool last = (t == nt - 2);
;             const char* a1 = cA + (size_t)(t + 1) * kstep;
;             const char* a2 = last ? nA : cA + (size_t)(t + 2) * kstep; const char* b2 = last ? nB : cB + (size_t)(t + 2) * kstep;
;             const char* a3 = a2 + kstep; const char* b3 = b2 + kstep;
;     ...
; #pragma unroll
;         for (int a = 0; a < 2; ++a)
; #pragma unroll
;             for (int b = 0; b < 2; ++b)
; #pragma unroll
;                 for (int m = 0; m < 4; ++m)
; #pragma unroll
;                     for (int n = 0; n < 2; ++n) acc[a][b][m][n] = (f32x4){0.f, 0.f, 0.f, 0.f};
.LBB0_996:
	s_ashr_i32 s35, s34, 31
	s_lshl_b64 s[36:37], s[34:35], 19
	s_add_u32 s36, s42, s36
	s_addc_u32 s37, s43, s37
	s_and_b64 s[38:39], s[0:1], exec
	s_cselect_b32 s35, s37, s41
	s_cselect_b32 s46, s36, s40
	s_ashr_i32 s23, s22, 31
	s_lshl_b64 s[38:39], s[22:23], 19
	s_add_u32 s38, s3, s38
	s_addc_u32 s39, s25, s39
	s_and_b64 s[56:57], s[0:1], exec
	s_cselect_b32 s23, s39, s53
	s_cselect_b32 s47, s38, s52
	s_add_u32 s40, s40, 0x40080
	s_addc_u32 s41, s41, 0
	s_add_u32 s75, s52, 0x100
	v_mov_b32_e32 v0, 0
	s_addc_u32 s76, s53, 0
	s_mov_b32 s77, -2
	v_mov_b32_e32 v1, v0
	v_pk_mov_b32 v[2:3], v[0:1], v[0:1]
	v_pk_mov_b32 v[4:5], v[0:1], v[0:1]
	v_pk_mov_b32 v[6:7], v[0:1], v[0:1]
	v_pk_mov_b32 v[8:9], v[0:1], v[0:1]
	v_pk_mov_b32 v[10:11], v[0:1], v[0:1]
	v_pk_mov_b32 v[12:13], v[0:1], v[0:1]
	v_pk_mov_b32 v[14:15], v[0:1], v[0:1]
	v_pk_mov_b32 v[16:17], v[0:1], v[0:1]
	v_pk_mov_b32 v[18:19], v[0:1], v[0:1]
	v_pk_mov_b32 v[20:21], v[0:1], v[0:1]
	v_pk_mov_b32 v[22:23], v[0:1], v[0:1]
	v_pk_mov_b32 v[24:25], v[0:1], v[0:1]
	v_pk_mov_b32 v[26:27], v[0:1], v[0:1]
	v_pk_mov_b32 v[28:29], v[0:1], v[0:1]
	v_pk_mov_b32 v[30:31], v[0:1], v[0:1]
	v_pk_mov_b32 v[32:33], v[0:1], v[0:1]
	v_pk_mov_b32 v[34:35], v[0:1], v[0:1]
	v_pk_mov_b32 v[36:37], v[0:1], v[0:1]
	v_pk_mov_b32 v[38:39], v[0:1], v[0:1]
	v_pk_mov_b32 v[40:41], v[0:1], v[0:1]
	v_pk_mov_b32 v[42:43], v[0:1], v[0:1]
	v_pk_mov_b32 v[44:45], v[0:1], v[0:1]
	v_pk_mov_b32 v[46:47], v[0:1], v[0:1]
	v_pk_mov_b32 v[48:49], v[0:1], v[0:1]
	v_pk_mov_b32 v[50:51], v[0:1], v[0:1]
	v_pk_mov_b32 v[52:53], v[0:1], v[0:1]
	v_pk_mov_b32 v[54:55], v[0:1], v[0:1]
	v_pk_mov_b32 v[56:57], v[0:1], v[0:1]
	v_pk_mov_b32 v[58:59], v[0:1], v[0:1]
	s_waitcnt vmcnt(0)
	v_pk_mov_b32 v[60:61], v[0:1], v[0:1]
	v_pk_mov_b32 v[62:63], v[0:1], v[0:1]
	v_pk_mov_b32 v[64:65], v[0:1], v[0:1]
	v_pk_mov_b32 v[66:67], v[0:1], v[0:1]
	v_pk_mov_b32 v[68:69], v[0:1], v[0:1]
	v_pk_mov_b32 v[70:71], v[0:1], v[0:1]
	v_pk_mov_b32 v[72:73], v[0:1], v[0:1]
	v_pk_mov_b32 v[74:75], v[0:1], v[0:1]
	v_pk_mov_b32 v[76:77], v[0:1], v[0:1]
	v_pk_mov_b32 v[78:79], v[0:1], v[0:1]
	v_pk_mov_b32 v[80:81], v[0:1], v[0:1]
	v_pk_mov_b32 v[82:83], v[0:1], v[0:1]
	v_pk_mov_b32 v[84:85], v[0:1], v[0:1]
	v_pk_mov_b32 v[86:87], v[0:1], v[0:1]
	v_pk_mov_b32 v[88:89], v[0:1], v[0:1]
	v_pk_mov_b32 v[90:91], v[0:1], v[0:1]
	v_pk_mov_b32 v[92:93], v[0:1], v[0:1]
	v_pk_mov_b32 v[94:95], v[0:1], v[0:1]
	v_pk_mov_b32 v[96:97], v[0:1], v[0:1]
	v_pk_mov_b32 v[98:99], v[0:1], v[0:1]
	v_pk_mov_b32 v[100:101], v[0:1], v[0:1]
	v_pk_mov_b32 v[102:103], v[0:1], v[0:1]
	v_pk_mov_b32 v[104:105], v[0:1], v[0:1]
	v_pk_mov_b32 v[106:107], v[0:1], v[0:1]
	v_pk_mov_b32 v[108:109], v[0:1], v[0:1]
	v_pk_mov_b32 v[110:111], v[0:1], v[0:1]
	v_pk_mov_b32 v[112:113], v[0:1], v[0:1]
	v_pk_mov_b32 v[114:115], v[0:1], v[0:1]
	v_pk_mov_b32 v[116:117], v[0:1], v[0:1]
	v_pk_mov_b32 v[118:119], v[0:1], v[0:1]
	v_pk_mov_b32 v[120:121], v[0:1], v[0:1]
	v_pk_mov_b32 v[122:123], v[0:1], v[0:1]
	v_pk_mov_b32 v[124:125], v[0:1], v[0:1]
	v_pk_mov_b32 v[126:127], v[0:1], v[0:1]

; template <class Epi>
; __device__ __forceinline__ void gemm_phase(LAS unsigned char* lds, const Gemm g, const StaticOrder& S, const Epi& E) {
;     ...
;             const char* a1 = cA + (size_t)(t + 1) * kstep;
;             const char* a2 = last ? nA : cA + (size_t)(t + 2) * kstep; const char* b2 = last ? nB : cB + (size_t)(t + 2) * kstep;
;     ...
; #pragma unroll
;         for (int a = 0; a < 2; ++a)
; #pragma unroll
;             for (int b = 0; b < 2; ++b)
; #pragma unroll
;                 for (int m = 0; m < 4; ++m)
; #pragma unroll
;                     for (int n = 0; n < 2; ++n) acc[a][b][m][n] = (f32x4){0.f, 0.f, 0.f, 0.f};
.LBB0_1088:
	s_add_u32 s46, s60, 0x100
	v_mov_b32_e32 v0, 0
	s_addc_u32 s47, s61, 0
	s_mov_b32 s83, -2
	v_mov_b32_e32 v1, v0
	v_pk_mov_b32 v[2:3], v[0:1], v[0:1]
	v_pk_mov_b32 v[4:5], v[0:1], v[0:1]
	v_pk_mov_b32 v[6:7], v[0:1], v[0:1]
	v_pk_mov_b32 v[8:9], v[0:1], v[0:1]
	v_pk_mov_b32 v[10:11], v[0:1], v[0:1]
	v_pk_mov_b32 v[12:13], v[0:1], v[0:1]
	v_pk_mov_b32 v[14:15], v[0:1], v[0:1]
	v_pk_mov_b32 v[16:17], v[0:1], v[0:1]
	v_pk_mov_b32 v[18:19], v[0:1], v[0:1]
	v_pk_mov_b32 v[20:21], v[0:1], v[0:1]
	v_pk_mov_b32 v[22:23], v[0:1], v[0:1]
	v_pk_mov_b32 v[24:25], v[0:1], v[0:1]
	v_pk_mov_b32 v[26:27], v[0:1], v[0:1]
	v_pk_mov_b32 v[28:29], v[0:1], v[0:1]
	v_pk_mov_b32 v[30:31], v[0:1], v[0:1]
	v_pk_mov_b32 v[32:33], v[0:1], v[0:1]
	v_pk_mov_b32 v[34:35], v[0:1], v[0:1]
	v_pk_mov_b32 v[36:37], v[0:1], v[0:1]
	v_pk_mov_b32 v[38:39], v[0:1], v[0:1]
	v_pk_mov_b32 v[40:41], v[0:1], v[0:1]
	v_pk_mov_b32 v[42:43], v[0:1], v[0:1]
	v_pk_mov_b32 v[44:45], v[0:1], v[0:1]
	v_pk_mov_b32 v[46:47], v[0:1], v[0:1]
	v_pk_mov_b32 v[48:49], v[0:1], v[0:1]
	v_pk_mov_b32 v[50:51], v[0:1], v[0:1]
	v_pk_mov_b32 v[52:53], v[0:1], v[0:1]
	v_pk_mov_b32 v[54:55], v[0:1], v[0:1]
	v_pk_mov_b32 v[56:57], v[0:1], v[0:1]
	v_pk_mov_b32 v[58:59], v[0:1], v[0:1]
	s_waitcnt vmcnt(0)
	v_pk_mov_b32 v[84:85], v[0:1], v[0:1]
	v_pk_mov_b32 v[86:87], v[0:1], v[0:1]
	v_pk_mov_b32 v[96:97], v[0:1], v[0:1]
	v_pk_mov_b32 v[98:99], v[0:1], v[0:1]
	v_pk_mov_b32 v[100:101], v[0:1], v[0:1]
	v_pk_mov_b32 v[102:103], v[0:1], v[0:1]
	v_pk_mov_b32 v[104:105], v[0:1], v[0:1]
	v_pk_mov_b32 v[106:107], v[0:1], v[0:1]
	v_pk_mov_b32 v[108:109], v[0:1], v[0:1]
	v_pk_mov_b32 v[110:111], v[0:1], v[0:1]
	v_pk_mov_b32 v[112:113], v[0:1], v[0:1]
	v_pk_mov_b32 v[114:115], v[0:1], v[0:1]
	v_pk_mov_b32 v[116:117], v[0:1], v[0:1]
	v_pk_mov_b32 v[118:119], v[0:1], v[0:1]
	v_pk_mov_b32 v[120:121], v[0:1], v[0:1]
	v_pk_mov_b32 v[122:123], v[0:1], v[0:1]
	v_pk_mov_b32 v[124:125], v[0:1], v[0:1]
	v_pk_mov_b32 v[126:127], v[0:1], v[0:1]
	v_pk_mov_b32 v[128:129], v[0:1], v[0:1]
	v_pk_mov_b32 v[130:131], v[0:1], v[0:1]
	v_pk_mov_b32 v[132:133], v[0:1], v[0:1]
	v_pk_mov_b32 v[134:135], v[0:1], v[0:1]
	v_pk_mov_b32 v[136:137], v[0:1], v[0:1]
	v_pk_mov_b32 v[138:139], v[0:1], v[0:1]
	v_pk_mov_b32 v[140:141], v[0:1], v[0:1]
	v_pk_mov_b32 v[142:143], v[0:1], v[0:1]
	v_pk_mov_b32 v[144:145], v[0:1], v[0:1]
	v_pk_mov_b32 v[146:147], v[0:1], v[0:1]
	v_pk_mov_b32 v[148:149], v[0:1], v[0:1]
	v_pk_mov_b32 v[150:151], v[0:1], v[0:1]
	v_pk_mov_b32 v[152:153], v[0:1], v[0:1]
	v_pk_mov_b32 v[154:155], v[0:1], v[0:1]
	v_pk_mov_b32 v[156:157], v[0:1], v[0:1]
	v_pk_mov_b32 v[158:159], v[0:1], v[0:1]

; template <class Epi>
; __device__ __forceinline__ void gemm_phase(LAS unsigned char* lds, const Gemm g, const StaticOrder& S, const Epi& E) {
;     ...
;         const char* nA = has_next ? (const char*)g.A + (size_t)nxt.pm * tstepA : cA; const char* nB = has_next ? (const char*)g.Bt + (size_t)nxt.pn * tstepB : cB;
;         for (int t = 0; t < nt; t += 2) {
;             const bool last = (t == nt - 2);
;             const char* a1 = cA + (size_t)(t + 1) * kstep;
;             const char* a2 = last ? nA : cA + (size_t)(t + 2) * kstep; const char* b2 = last ? nB : cB + (size_t)(t + 2) * kstep;
;             const char* a3 = a2 + kstep; const char* b3 = b2 + kstep;
;     ...
; #pragma unroll
;         for (int a = 0; a < 2; ++a)
; #pragma unroll
;             for (int b = 0; b < 2; ++b)
; #pragma unroll
;                 for (int m = 0; m < 4; ++m)
; #pragma unroll
;                     for (int n = 0; n < 2; ++n) acc[a][b][m][n] = (f32x4){0.f, 0.f, 0.f, 0.f};
.LBB0_1368:
	s_ashr_i32 s23, s22, 31
	s_lshl_b64 s[34:35], s[22:23], 19
	s_add_u32 s34, s42, s34
	s_addc_u32 s35, s43, s35
	s_and_b64 s[36:37], s[0:1], exec
	s_cselect_b32 s13, s35, s41
	s_cselect_b32 s23, s34, s40
	s_ashr_i32 s21, s20, 31
	s_lshl_b64 s[36:37], s[20:21], 19
	s_add_u32 s36, s28, s36
	s_addc_u32 s37, s29, s37
	s_and_b64 s[46:47], s[0:1], exec
	s_cselect_b32 s21, s37, s53
	s_cselect_b32 s39, s36, s52
	s_add_u32 s40, s40, 0x40080
	s_addc_u32 s41, s41, 0
	s_add_u32 s46, s52, 0x100
	v_mov_b32_e32 v0, 0
	s_addc_u32 s47, s53, 0
	s_mov_b32 s73, -2
	v_mov_b32_e32 v1, v0
	v_pk_mov_b32 v[2:3], v[0:1], v[0:1]
	v_pk_mov_b32 v[4:5], v[0:1], v[0:1]
	v_pk_mov_b32 v[6:7], v[0:1], v[0:1]
	v_pk_mov_b32 v[8:9], v[0:1], v[0:1]
	v_pk_mov_b32 v[10:11], v[0:1], v[0:1]
	v_pk_mov_b32 v[12:13], v[0:1], v[0:1]
	v_pk_mov_b32 v[14:15], v[0:1], v[0:1]
	v_pk_mov_b32 v[16:17], v[0:1], v[0:1]
	v_pk_mov_b32 v[18:19], v[0:1], v[0:1]
	v_pk_mov_b32 v[20:21], v[0:1], v[0:1]
	v_pk_mov_b32 v[22:23], v[0:1], v[0:1]
	v_pk_mov_b32 v[24:25], v[0:1], v[0:1]
	v_pk_mov_b32 v[26:27], v[0:1], v[0:1]
	v_pk_mov_b32 v[28:29], v[0:1], v[0:1]
	v_pk_mov_b32 v[30:31], v[0:1], v[0:1]
	v_pk_mov_b32 v[32:33], v[0:1], v[0:1]
	v_pk_mov_b32 v[34:35], v[0:1], v[0:1]
	v_pk_mov_b32 v[36:37], v[0:1], v[0:1]
	v_pk_mov_b32 v[38:39], v[0:1], v[0:1]
	v_pk_mov_b32 v[40:41], v[0:1], v[0:1]
	v_pk_mov_b32 v[42:43], v[0:1], v[0:1]
	v_pk_mov_b32 v[44:45], v[0:1], v[0:1]
	v_pk_mov_b32 v[46:47], v[0:1], v[0:1]
	v_pk_mov_b32 v[48:49], v[0:1], v[0:1]
	v_pk_mov_b32 v[50:51], v[0:1], v[0:1]
	v_pk_mov_b32 v[52:53], v[0:1], v[0:1]
	v_pk_mov_b32 v[54:55], v[0:1], v[0:1]
	v_pk_mov_b32 v[56:57], v[0:1], v[0:1]
	v_pk_mov_b32 v[58:59], v[0:1], v[0:1]
	s_waitcnt vmcnt(0)
	v_pk_mov_b32 v[60:61], v[0:1], v[0:1]
	v_pk_mov_b32 v[62:63], v[0:1], v[0:1]
	v_pk_mov_b32 v[64:65], v[0:1], v[0:1]
	v_pk_mov_b32 v[66:67], v[0:1], v[0:1]
	v_pk_mov_b32 v[68:69], v[0:1], v[0:1]
	v_pk_mov_b32 v[70:71], v[0:1], v[0:1]
	v_pk_mov_b32 v[72:73], v[0:1], v[0:1]
	v_pk_mov_b32 v[74:75], v[0:1], v[0:1]
	v_pk_mov_b32 v[76:77], v[0:1], v[0:1]
	v_pk_mov_b32 v[78:79], v[0:1], v[0:1]
	v_pk_mov_b32 v[80:81], v[0:1], v[0:1]
	v_pk_mov_b32 v[82:83], v[0:1], v[0:1]
	v_pk_mov_b32 v[84:85], v[0:1], v[0:1]
	v_pk_mov_b32 v[86:87], v[0:1], v[0:1]
	v_pk_mov_b32 v[96:97], v[0:1], v[0:1]
	v_pk_mov_b32 v[98:99], v[0:1], v[0:1]
	v_pk_mov_b32 v[100:101], v[0:1], v[0:1]
	v_pk_mov_b32 v[102:103], v[0:1], v[0:1]
	v_pk_mov_b32 v[112:113], v[0:1], v[0:1]
	v_pk_mov_b32 v[114:115], v[0:1], v[0:1]
	v_pk_mov_b32 v[116:117], v[0:1], v[0:1]
	v_pk_mov_b32 v[118:119], v[0:1], v[0:1]
	v_pk_mov_b32 v[120:121], v[0:1], v[0:1]
	v_pk_mov_b32 v[122:123], v[0:1], v[0:1]
	v_pk_mov_b32 v[124:125], v[0:1], v[0:1]
	v_pk_mov_b32 v[126:127], v[0:1], v[0:1]
	v_pk_mov_b32 v[128:129], v[0:1], v[0:1]
	v_pk_mov_b32 v[130:131], v[0:1], v[0:1]
	v_pk_mov_b32 v[132:133], v[0:1], v[0:1]
	v_pk_mov_b32 v[134:135], v[0:1], v[0:1]
	v_pk_mov_b32 v[136:137], v[0:1], v[0:1]
	v_pk_mov_b32 v[138:139], v[0:1], v[0:1]
	v_pk_mov_b32 v[140:141], v[0:1], v[0:1]
	v_pk_mov_b32 v[142:143], v[0:1], v[0:1]
